# v37 + latent HGRN state fold: both segments of a pair have their loads in flight together (one round trip per pair instead of per segment)
# baseline (speedup 1.0000x reference)
.LBB0_792:
	v_lshl_add_u64 v[108:109], s[78:79], 0, v[90:91]
	v_add_co_u32_e32 v144, vcc, s3, v108
	v_lshl_add_u64 v[106:107], s[78:79], 0, v[74:75]
	s_nop 0
	v_addc_co_u32_e32 v145, vcc, 0, v109, vcc
	s_mov_b32 s6, 0x45600000
	v_add_co_u32_e32 v162, vcc, s6, v106
	v_lshl_add_u64 v[102:103], s[78:79], 0, v[86:87]
	s_nop 0
	v_addc_co_u32_e32 v163, vcc, 0, v107, vcc
	v_add_co_u32_e32 v164, vcc, s3, v102
	v_lshl_add_u64 v[100:101], s[78:79], 0, v[84:85]
	s_nop 0
	v_addc_co_u32_e32 v165, vcc, 0, v103, vcc
	v_add_co_u32_e32 v170, vcc, s3, v100
	v_lshl_add_u64 v[98:99], s[78:79], 0, v[82:83]
	s_nop 0
	v_addc_co_u32_e32 v171, vcc, 0, v101, vcc
	v_add_co_u32_e32 v140, vcc, s3, v98
	v_lshl_add_u64 v[96:97], s[78:79], 0, v[80:81]
	s_nop 0
	v_addc_co_u32_e32 v141, vcc, 0, v99, vcc
	v_add_co_u32_e32 v172, vcc, s3, v96
	v_lshl_add_u64 v[94:95], s[78:79], 0, v[78:79]
	s_nop 0
	v_addc_co_u32_e32 v173, vcc, 0, v97, vcc
	v_add_co_u32_e32 v120, vcc, s3, v94
	v_lshl_add_u64 v[92:93], s[78:79], 0, v[76:77]
	s_nop 0
	v_addc_co_u32_e32 v121, vcc, 0, v95, vcc
	v_add_co_u32_e32 v124, vcc, s3, v92
	v_lshl_add_u64 v[104:105], s[78:79], 0, v[88:89]
	s_nop 0
	v_addc_co_u32_e32 v125, vcc, 0, v93, vcc
	global_load_dwordx4 v[112:115], v[162:163], off offset:384
	global_load_dwordx4 v[116:119], v[162:163], off offset:320
	s_nop 0
	global_load_dwordx4 v[120:123], v[120:121], off
	s_nop 0
	global_load_dwordx4 v[124:127], v[124:125], off
	s_nop 0
	global_load_dwordx4 v[128:131], v[162:163], off
	global_load_dwordx4 v[132:135], v[162:163], off offset:128
	global_load_dwordx4 v[136:139], v[162:163], off offset:64
	s_nop 0
	global_load_dwordx4 v[140:143], v[140:141], off
	s_nop 0
	global_load_dwordx4 v[176:179], v[172:173], off
	global_load_dwordx4 v[180:183], v[162:163], off offset:256
	global_load_dwordx4 v[186:189], v[162:163], off offset:192
	global_load_dwordx4 v[190:193], v[164:165], off
	global_load_dwordx4 v[194:197], v[170:171], off
	v_add_co_u32_e32 v164, vcc, s3, v104
	s_add_i32 s6, s5, 1
	s_nop 0
	v_addc_co_u32_e32 v165, vcc, 0, v105, vcc
	global_load_dwordx4 v[198:201], v[164:165], off
	global_load_dwordx4 v[202:205], v[144:145], off
	global_load_dwordx4 v[226:229], v[162:163], off offset:448
	s_cmp_ge_u32 s6, s9
	s_cbranch_scc1 .Lfold_eo
	global_load_dwordx4 v[32:35], v[162:163], off offset:640
	v_add_co_u32_e32 v246, vcc, 0x44610000, v96
	s_nop 1
	v_addc_co_u32_e32 v247, vcc, 0, v97, vcc
	s_nop 0
	global_load_dwordx4 v[36:39], v[246:247], off
	global_load_dwordx4 v[40:43], v[162:163], off offset:704
	v_add_co_u32_e32 v246, vcc, 0x44610000, v98
	s_nop 1
	v_addc_co_u32_e32 v247, vcc, 0, v99, vcc
	s_nop 0
	global_load_dwordx4 v[44:47], v[246:247], off
	global_load_dwordx4 v[48:51], v[162:163], off offset:768
	v_add_co_u32_e32 v246, vcc, 0x44610000, v100
	s_nop 1
	v_addc_co_u32_e32 v247, vcc, 0, v101, vcc
	s_nop 0
	global_load_dwordx4 v[52:55], v[246:247], off
	global_load_dwordx4 v[56:59], v[162:163], off offset:832
	v_add_co_u32_e32 v246, vcc, 0x44610000, v102
	s_nop 1
	v_addc_co_u32_e32 v247, vcc, 0, v103, vcc
	s_nop 0
	global_load_dwordx4 v[60:63], v[246:247], off
	global_load_dwordx4 v[234:237], v[162:163], off offset:896
	v_add_co_u32_e32 v246, vcc, 0x44610000, v104
	s_nop 1
	v_addc_co_u32_e32 v247, vcc, 0, v105, vcc
	s_nop 0
	global_load_dwordx4 v[238:241], v[246:247], off
	global_load_dwordx4 v[242:245], v[162:163], off offset:960
	v_add_co_u32_e32 v246, vcc, 0x44610000, v108
	s_nop 1
	v_addc_co_u32_e32 v247, vcc, 0, v109, vcc
	s_nop 0
	global_load_dwordx4 v[170:173], v[246:247], off
	s_waitcnt vmcnt(23)
	v_pk_fma_f32 v[2:3], v[2:3], v[130:131], v[126:127]
	v_pk_fma_f32 v[0:1], v[0:1], v[128:129], v[124:125]
	s_waitcnt vmcnt(21)
	v_pk_fma_f32 v[6:7], v[6:7], v[138:139], v[122:123]
	v_pk_fma_f32 v[4:5], v[4:5], v[136:137], v[120:121]
	global_load_dwordx4 v[128:131], v[162:163], off offset:512
	v_add_co_u32_e32 v246, vcc, 0x44610000, v92
	s_nop 1
	v_addc_co_u32_e32 v247, vcc, 0, v93, vcc
	s_nop 0
	global_load_dwordx4 v[124:127], v[246:247], off
	global_load_dwordx4 v[136:139], v[162:163], off offset:576
	v_add_co_u32_e32 v246, vcc, 0x44610000, v94
	s_nop 1
	v_addc_co_u32_e32 v247, vcc, 0, v95, vcc
	s_nop 0
	global_load_dwordx4 v[120:123], v[246:247], off
	s_waitcnt vmcnt(23)
	v_pk_fma_f32 v[10:11], v[10:11], v[134:135], v[178:179]
	v_pk_fma_f32 v[8:9], v[8:9], v[132:133], v[176:177]
	s_waitcnt vmcnt(21)
	v_pk_fma_f32 v[14:15], v[14:15], v[188:189], v[142:143]
	v_pk_fma_f32 v[12:13], v[12:13], v[186:187], v[140:141]
	s_waitcnt vmcnt(19)
	v_pk_fma_f32 v[18:19], v[18:19], v[182:183], v[196:197]
	v_pk_fma_f32 v[16:17], v[16:17], v[180:181], v[194:195]
	v_pk_fma_f32 v[22:23], v[22:23], v[118:119], v[192:193]
	v_pk_fma_f32 v[20:21], v[20:21], v[116:117], v[190:191]
	s_waitcnt vmcnt(18)
	v_pk_fma_f32 v[26:27], v[26:27], v[114:115], v[200:201]
	v_pk_fma_f32 v[24:25], v[24:25], v[112:113], v[198:199]
	s_waitcnt vmcnt(16)
	v_pk_fma_f32 v[30:31], v[30:31], v[228:229], v[204:205]
	v_pk_fma_f32 v[28:29], v[28:29], v[226:227], v[202:203]
	s_waitcnt vmcnt(14)
	v_pk_fma_f32 v[10:11], v[10:11], v[34:35], v[38:39]
	v_pk_fma_f32 v[8:9], v[8:9], v[32:33], v[36:37]
	s_waitcnt vmcnt(12)
	v_pk_fma_f32 v[14:15], v[14:15], v[42:43], v[46:47]
	v_pk_fma_f32 v[12:13], v[12:13], v[40:41], v[44:45]
	s_waitcnt vmcnt(10)
	v_pk_fma_f32 v[18:19], v[18:19], v[50:51], v[54:55]
	v_pk_fma_f32 v[16:17], v[16:17], v[48:49], v[52:53]
	s_waitcnt vmcnt(8)
	v_pk_fma_f32 v[22:23], v[22:23], v[58:59], v[62:63]
	v_pk_fma_f32 v[20:21], v[20:21], v[56:57], v[60:61]
	s_waitcnt vmcnt(6)
	v_pk_fma_f32 v[26:27], v[26:27], v[236:237], v[240:241]
	v_pk_fma_f32 v[24:25], v[24:25], v[234:235], v[238:239]
	s_waitcnt vmcnt(4)
	v_pk_fma_f32 v[30:31], v[30:31], v[244:245], v[172:173]
	v_pk_fma_f32 v[28:29], v[28:29], v[242:243], v[170:171]
	s_waitcnt vmcnt(2)
	v_pk_fma_f32 v[2:3], v[2:3], v[130:131], v[126:127]
	v_pk_fma_f32 v[0:1], v[0:1], v[128:129], v[124:125]
	s_waitcnt vmcnt(0)
	v_pk_fma_f32 v[6:7], v[6:7], v[138:139], v[122:123]
	v_pk_fma_f32 v[4:5], v[4:5], v[136:137], v[120:121]
	s_branch .LBB0_791
.Lfold_eo:
	s_waitcnt vmcnt(11)
	v_pk_fma_f32 v[2:3], v[2:3], v[130:131], v[126:127]
	v_pk_fma_f32 v[0:1], v[0:1], v[128:129], v[124:125]
	s_waitcnt vmcnt(9)
	v_pk_fma_f32 v[6:7], v[6:7], v[138:139], v[122:123]
	v_pk_fma_f32 v[4:5], v[4:5], v[136:137], v[120:121]
	s_waitcnt vmcnt(7)
	v_pk_fma_f32 v[10:11], v[10:11], v[134:135], v[178:179]
	v_pk_fma_f32 v[8:9], v[8:9], v[132:133], v[176:177]
	s_waitcnt vmcnt(5)
	v_pk_fma_f32 v[14:15], v[14:15], v[188:189], v[142:143]
	v_pk_fma_f32 v[12:13], v[12:13], v[186:187], v[140:141]
	s_waitcnt vmcnt(3)
	v_pk_fma_f32 v[18:19], v[18:19], v[182:183], v[196:197]
	v_pk_fma_f32 v[16:17], v[16:17], v[180:181], v[194:195]
	v_pk_fma_f32 v[22:23], v[22:23], v[118:119], v[192:193]
	v_pk_fma_f32 v[20:21], v[20:21], v[116:117], v[190:191]
	s_waitcnt vmcnt(2)
	v_pk_fma_f32 v[26:27], v[26:27], v[114:115], v[200:201]
	v_pk_fma_f32 v[24:25], v[24:25], v[112:113], v[198:199]
	s_waitcnt vmcnt(0)
	v_pk_fma_f32 v[30:31], v[30:31], v[228:229], v[204:205]
	v_pk_fma_f32 v[28:29], v[28:29], v[226:227], v[202:203]
	s_branch .LBB0_791
